# top-k compaction leaves after the last populated ballot row (cur<66: row 0 only, cur<130: rows 0-1), on top of the bit-27 start and row-specialised search
# speedup vs baseline: 1.0083x; 1.0083x over previous
; __device__ __forceinline__ void phase_cmp(const Params& p, LAS unsigned char* lds, const bf16_t* Z, const float* G, const bf16_t* KC, const bf16_t* ACCW, float* ACC, int* IDX, ...
;     ...
; #pragma unroll
;                 for (int i = 0; i < 4; ++i) {
;                     const bool gt = ok[i] && v[i] > T, eq = ok[i] && v[i] == T;
;                     const unsigned long long mg = __ballot(gt), me = __ballot(eq);
;                     const int rg = __builtin_amdgcn_mbcnt_hi((unsigned)(mg >> 32), __builtin_amdgcn_mbcnt_lo((unsigned)mg, 0u));
;                     const int re = __builtin_amdgcn_mbcnt_hi((unsigned)(me >> 32), __builtin_amdgcn_mbcnt_lo((unsigned)me, 0u));
;                     if (gt) dst[pos_gt + rg] = lane + 64 * i;
;                     if (eq && eq_seen + re < need) dst[eq_base + eq_seen + re] = lane + 64 * i;
;                     pos_gt += __builtin_popcountll(mg); eq_seen += __builtin_popcountll(me);
;                 }
.LBB0_440:
	s_or_b64 exec, exec, s[22:23]
	s_cmp_lt_u32 s91, 66
	s_cbranch_scc1 .LBB0_423
	v_cmp_eq_u32_e64 s[22:23], s96, v5
	s_and_b64 s[38:39], vcc, s[22:23]
	v_cndmask_b32_e64 v2, 0, 1, s[38:39]
	s_bcnt1_i32_b64 s81, s[42:43]
	v_cmp_ne_u32_e64 s[24:25], 0, v8
	v_cmp_ne_u32_e64 s[22:23], 0, v2
	s_and_saveexec_b64 s[42:43], s[78:79]
	s_cbranch_execz .LBB0_442
	v_mbcnt_lo_u32_b32 v2, s24, 0
	v_mbcnt_hi_u32_b32 v2, s25, v2
	v_add_lshl_u32 v2, v2, s81, 2
	global_store_dword v2, v127, s[72:73] offset:12

; __device__ __forceinline__ void phase_cmp(const Params& p, LAS unsigned char* lds, const bf16_t* Z, const float* G, const bf16_t* KC, const bf16_t* ACCW, float* ACC, int* IDX, ...
;     ...
; #pragma unroll
;                 for (int i = 0; i < 4; ++i) {
;                     const bool gt = ok[i] && v[i] > T, eq = ok[i] && v[i] == T;
;                     const unsigned long long mg = __ballot(gt), me = __ballot(eq);
;                     const int rg = __builtin_amdgcn_mbcnt_hi((unsigned)(mg >> 32), __builtin_amdgcn_mbcnt_lo((unsigned)mg, 0u));
;                     const int re = __builtin_amdgcn_mbcnt_hi((unsigned)(me >> 32), __builtin_amdgcn_mbcnt_lo((unsigned)me, 0u));
;                     if (gt) dst[pos_gt + rg] = lane + 64 * i;
;                     if (eq && eq_seen + re < need) dst[eq_base + eq_seen + re] = lane + 64 * i;
;                     pos_gt += __builtin_popcountll(mg); eq_seen += __builtin_popcountll(me);
;                 }
.LBB0_444:
	s_or_b64 exec, exec, s[20:21]
	s_cmpk_lt_u32 s91, 0x82
	s_cbranch_scc1 .LBB0_423
	v_cmp_eq_u32_e64 s[20:21], s96, v4
	s_and_b64 s[38:39], s[16:17], s[20:21]
	v_cndmask_b32_e64 v2, 0, 1, s[38:39]
	s_bcnt1_i32_b64 s78, s[24:25]
	v_cmp_ne_u32_e64 s[24:25], 0, v7
	v_cmp_ne_u32_e64 s[20:21], 0, v2
	s_and_saveexec_b64 s[42:43], s[76:77]
	s_cbranch_execz .LBB0_446
	v_mbcnt_lo_u32_b32 v2, s24, 0
	v_mbcnt_hi_u32_b32 v2, s25, v2
	s_add_i32 s41, s81, s78
	v_add_lshl_u32 v2, v2, s41, 2
	global_store_dword v2, v129, s[72:73] offset:12
